# gate/up epilogue SwiGLU as interleaved chains without compiler shuffles (on top of peeled GEMM loops)
# speedup vs baseline: 1.0153x; 1.0153x over previous
.LBB0_788:
	s_waitcnt lgkmcnt(0)
	v_mul_f32_e32 v12, v12, v16
	v_mul_f32_e32 v13, v13, v16
	v_mul_f32_e32 v14, v14, v16
	v_mul_f32_e32 v15, v15, v16
	v_mul_f32_e32 v4, v4, v16
	v_mul_f32_e32 v5, v5, v16
	v_mul_f32_e32 v6, v6, v16
	v_mul_f32_e32 v7, v7, v16
	v_mul_f32_e32 v8, v8, v16
	v_mul_f32_e32 v9, v9, v16
	v_mul_f32_e32 v10, v10, v16
	v_mul_f32_e32 v11, v11, v16
	v_mul_f32_e32 v0, v0, v16
	v_mul_f32_e32 v1, v1, v16
	v_mul_f32_e32 v2, v2, v16
	v_mul_f32_e32 v3, v3, v16
	v_mul_f32_e32 v8, v8, v12
	v_mul_f32_e32 v9, v9, v13
	v_mul_f32_e32 v10, v10, v14
	v_mul_f32_e32 v11, v11, v15
	v_mul_f32_e32 v0, v0, v4
	v_mul_f32_e32 v1, v1, v5
	v_mul_f32_e32 v2, v2, v6
	v_mul_f32_e32 v3, v3, v7
	v_mul_f32_e32 v12, 0xbfb8aa3b, v12
	v_mul_f32_e32 v13, 0xbfb8aa3b, v13
	v_mul_f32_e32 v14, 0xbfb8aa3b, v14
	v_mul_f32_e32 v15, 0xbfb8aa3b, v15
	v_mul_f32_e32 v4, 0xbfb8aa3b, v4
	v_mul_f32_e32 v5, 0xbfb8aa3b, v5
	v_mul_f32_e32 v6, 0xbfb8aa3b, v6
	v_mul_f32_e32 v7, 0xbfb8aa3b, v7
	v_exp_f32_e32 v12, v12
	v_exp_f32_e32 v13, v13
	v_exp_f32_e32 v14, v14
	v_exp_f32_e32 v15, v15
	v_exp_f32_e32 v4, v4
	v_exp_f32_e32 v5, v5
	v_exp_f32_e32 v6, v6
	v_exp_f32_e32 v7, v7
	v_add_f32_e32 v12, 1.0, v12
	v_add_f32_e32 v13, 1.0, v13
	v_add_f32_e32 v14, 1.0, v14
	v_add_f32_e32 v15, 1.0, v15
	v_add_f32_e32 v4, 1.0, v4
	v_add_f32_e32 v5, 1.0, v5
	v_add_f32_e32 v6, 1.0, v6
	v_add_f32_e32 v7, 1.0, v7
	v_rcp_f32_e32 v12, v12
	v_rcp_f32_e32 v13, v13
	v_rcp_f32_e32 v14, v14
	v_rcp_f32_e32 v15, v15
	v_rcp_f32_e32 v4, v4
	v_rcp_f32_e32 v5, v5
	v_rcp_f32_e32 v6, v6
	v_rcp_f32_e32 v7, v7
	v_mul_f32_e32 v8, v8, v12
	v_mul_f32_e32 v9, v9, v13
	v_mul_f32_e32 v10, v10, v14
	v_mul_f32_e32 v11, v11, v15
	v_mul_f32_e32 v0, v0, v4
	v_mul_f32_e32 v1, v1, v5
	v_mul_f32_e32 v2, v2, v6
	v_mul_f32_e32 v3, v3, v7
	v_cvt_pk_bf16_f32 v12, v8, v9
	v_cvt_pk_bf16_f32 v13, v10, v11
	v_cvt_pk_bf16_f32 v14, v0, v1
	v_cvt_pk_bf16_f32 v15, v2, v3
	s_and_b64 vcc, exec, s[6:7]
	s_mov_b32 s8, s18
	s_mov_b32 s28, s20
	s_mov_b64 s[62:63], s[24:25]
	s_mov_b64 s[58:59], s[22:23]
	v_add_u32_e32 v4, v17, v139
	v_mov_b32_e32 v5, 0x16000
	v_lshl_add_u32 v4, v4, 1, v5
	buffer_store_dwordx4 v[12:15], v4, s[36:39], 0 offen sc1
	s_cbranch_vccnz .LBB0_825

.LBB0_797:
	s_waitcnt lgkmcnt(0)
	v_mul_f32_e32 v124, v124, v140
	v_mul_f32_e32 v125, v125, v140
	v_mul_f32_e32 v126, v126, v140
	v_mul_f32_e32 v127, v127, v140
	v_mul_f32_e32 v116, v116, v140
	v_mul_f32_e32 v117, v117, v140
	v_mul_f32_e32 v118, v118, v140
	v_mul_f32_e32 v119, v119, v140
	v_mul_f32_e32 v120, v120, v140
	v_mul_f32_e32 v121, v121, v140
	v_mul_f32_e32 v122, v122, v140
	v_mul_f32_e32 v123, v123, v140
	v_mul_f32_e32 v112, v112, v140
	v_mul_f32_e32 v113, v113, v140
	v_mul_f32_e32 v114, v114, v140
	v_mul_f32_e32 v115, v115, v140
	v_mul_f32_e32 v120, v120, v124
	v_mul_f32_e32 v121, v121, v125
	v_mul_f32_e32 v122, v122, v126
	v_mul_f32_e32 v123, v123, v127
	v_mul_f32_e32 v112, v112, v116
	v_mul_f32_e32 v113, v113, v117
	v_mul_f32_e32 v114, v114, v118
	v_mul_f32_e32 v115, v115, v119
	v_mul_f32_e32 v124, 0xbfb8aa3b, v124
	v_mul_f32_e32 v125, 0xbfb8aa3b, v125
	v_mul_f32_e32 v126, 0xbfb8aa3b, v126
	v_mul_f32_e32 v127, 0xbfb8aa3b, v127
	v_mul_f32_e32 v116, 0xbfb8aa3b, v116
	v_mul_f32_e32 v117, 0xbfb8aa3b, v117
	v_mul_f32_e32 v118, 0xbfb8aa3b, v118
	v_mul_f32_e32 v119, 0xbfb8aa3b, v119
	v_exp_f32_e32 v124, v124
	v_exp_f32_e32 v125, v125
	v_exp_f32_e32 v126, v126
	v_exp_f32_e32 v127, v127
	v_exp_f32_e32 v116, v116
	v_exp_f32_e32 v117, v117
	v_exp_f32_e32 v118, v118
	v_exp_f32_e32 v119, v119
	v_add_f32_e32 v124, 1.0, v124
	v_add_f32_e32 v125, 1.0, v125
	v_add_f32_e32 v126, 1.0, v126
	v_add_f32_e32 v127, 1.0, v127
	v_add_f32_e32 v116, 1.0, v116
	v_add_f32_e32 v117, 1.0, v117
	v_add_f32_e32 v118, 1.0, v118
	v_add_f32_e32 v119, 1.0, v119
	v_rcp_f32_e32 v124, v124
	v_rcp_f32_e32 v125, v125
	v_rcp_f32_e32 v126, v126
	v_rcp_f32_e32 v127, v127
	v_rcp_f32_e32 v116, v116
	v_rcp_f32_e32 v117, v117
	v_rcp_f32_e32 v118, v118
	v_rcp_f32_e32 v119, v119
	v_mul_f32_e32 v120, v120, v124
	v_mul_f32_e32 v121, v121, v125
	v_mul_f32_e32 v122, v122, v126
	v_mul_f32_e32 v123, v123, v127
	v_mul_f32_e32 v112, v112, v116
	v_mul_f32_e32 v113, v113, v117
	v_mul_f32_e32 v114, v114, v118
	v_mul_f32_e32 v115, v115, v119
	v_cvt_pk_bf16_f32 v124, v120, v121
	v_cvt_pk_bf16_f32 v125, v122, v123
	v_cvt_pk_bf16_f32 v126, v112, v113
	v_cvt_pk_bf16_f32 v127, v114, v115
	s_movk_i32 s1, 0xb00
	v_lshl_or_b32 v139, s8, 7, v144
	s_mov_b64 s[58:59], -1
	s_andn2_b64 vcc, exec, s[28:29]
	v_mul_lo_u32 v113, v138, s1
	v_add_lshl_u32 v112, v113, v139, 1
	buffer_store_dwordx4 v[124:127], v112, s[36:39], 0 offen sc1
	v_cndmask_b32_e64 v112, 0, 1, s[28:29]
	v_cmp_ne_u32_e64 s[8:9], 1, v112
	v_or_b32_e32 v114, 16, v138
	s_cbranch_vccnz .LBB0_799
	v_ashrrev_i32_e32 v115, 31, v114
	v_lshlrev_b64 v[116:117], 6, v[114:115]
	v_lshl_add_u64 v[146:147], s[94:95], 0, v[116:117]
	global_load_dwordx4 v[116:119], v[146:147], off offset:48
	global_load_dwordx4 v[120:123], v[146:147], off offset:32
	global_load_dwordx4 v[124:127], v[146:147], off offset:16
	s_nop 0
	global_load_dwordx4 v[146:149], v[146:147], off
	s_mov_b64 s[58:59], 0
	s_waitcnt vmcnt(0)
	v_add_f32_e32 v120, v120, v121
	v_add_f32_e32 v122, v122, v123
	v_mov_b32_e32 v150, v147
	v_mov_b32_e32 v151, v148
	v_mov_b32_e32 v147, v149
	v_mov_b32_e32 v148, v125
	v_mov_b32_e32 v149, v126
	v_mov_b32_e32 v125, v127
	v_pk_add_f32 v[146:147], v[150:151], v[146:147]
	v_pk_add_f32 v[124:125], v[148:149], v[124:125]
	v_pk_add_f32 v[146:147], v[146:147], v[146:147] op_sel:[0,1] op_sel_hi:[1,0]
	v_pk_add_f32 v[124:125], v[124:125], v[124:125] op_sel:[0,1] op_sel_hi:[1,0]
	v_mov_b32_e32 v147, v116
	v_mov_b32_e32 v125, v117
	v_mov_b32_e32 v121, v118
	v_mov_b32_e32 v123, v119
	v_pk_add_f32 v[116:117], v[146:147], v[124:125]
	v_pk_add_f32 v[118:119], v[120:121], v[122:123]
	s_nop 0
	v_pk_add_f32 v[116:117], v[116:117], v[118:119]
	s_nop 0
	v_add_f32_e32 v112, v116, v117
	v_fmamk_f32 v112, v112, 0x3a800000, v193
	v_cmp_gt_f32_e32 vcc, s40, v112
	v_mul_f32_e32 v115, 0x4b800000, v112
	s_nop 0
	v_cndmask_b32_e32 v112, v112, v115, vcc
	v_rsq_f32_e32 v112, v112
	s_nop 0
	v_mul_f32_e32 v115, 0x45800000, v112
	v_cndmask_b32_e32 v112, v112, v115, vcc

.LBB0_801:
	s_waitcnt lgkmcnt(0)
	v_mul_f32_e32 v108, v108, v112
	v_mul_f32_e32 v109, v109, v112
	v_mul_f32_e32 v110, v110, v112
	v_mul_f32_e32 v111, v111, v112
	v_mul_f32_e32 v100, v100, v112
	v_mul_f32_e32 v101, v101, v112
	v_mul_f32_e32 v102, v102, v112
	v_mul_f32_e32 v103, v103, v112
	v_mul_f32_e32 v104, v104, v112
	v_mul_f32_e32 v105, v105, v112
	v_mul_f32_e32 v106, v106, v112
	v_mul_f32_e32 v107, v107, v112
	v_mul_f32_e32 v96, v96, v112
	v_mul_f32_e32 v97, v97, v112
	v_mul_f32_e32 v98, v98, v112
	v_mul_f32_e32 v99, v99, v112
	v_mul_f32_e32 v104, v104, v108
	v_mul_f32_e32 v105, v105, v109
	v_mul_f32_e32 v106, v106, v110
	v_mul_f32_e32 v107, v107, v111
	v_mul_f32_e32 v96, v96, v100
	v_mul_f32_e32 v97, v97, v101
	v_mul_f32_e32 v98, v98, v102
	v_mul_f32_e32 v99, v99, v103
	v_mul_f32_e32 v108, 0xbfb8aa3b, v108
	v_mul_f32_e32 v109, 0xbfb8aa3b, v109
	v_mul_f32_e32 v110, 0xbfb8aa3b, v110
	v_mul_f32_e32 v111, 0xbfb8aa3b, v111
	v_mul_f32_e32 v100, 0xbfb8aa3b, v100
	v_mul_f32_e32 v101, 0xbfb8aa3b, v101
	v_mul_f32_e32 v102, 0xbfb8aa3b, v102
	v_mul_f32_e32 v103, 0xbfb8aa3b, v103
	v_exp_f32_e32 v108, v108
	v_exp_f32_e32 v109, v109
	v_exp_f32_e32 v110, v110
	v_exp_f32_e32 v111, v111
	v_exp_f32_e32 v100, v100
	v_exp_f32_e32 v101, v101
	v_exp_f32_e32 v102, v102
	v_exp_f32_e32 v103, v103
	v_add_f32_e32 v108, 1.0, v108
	v_add_f32_e32 v109, 1.0, v109
	v_add_f32_e32 v110, 1.0, v110
	v_add_f32_e32 v111, 1.0, v111
	v_add_f32_e32 v100, 1.0, v100
	v_add_f32_e32 v101, 1.0, v101
	v_add_f32_e32 v102, 1.0, v102
	v_add_f32_e32 v103, 1.0, v103
	v_rcp_f32_e32 v108, v108
	v_rcp_f32_e32 v109, v109
	v_rcp_f32_e32 v110, v110
	v_rcp_f32_e32 v111, v111
	v_rcp_f32_e32 v100, v100
	v_rcp_f32_e32 v101, v101
	v_rcp_f32_e32 v102, v102
	v_rcp_f32_e32 v103, v103
	v_mul_f32_e32 v104, v104, v108
	v_mul_f32_e32 v105, v105, v109
	v_mul_f32_e32 v106, v106, v110
	v_mul_f32_e32 v107, v107, v111
	v_mul_f32_e32 v96, v96, v100
	v_mul_f32_e32 v97, v97, v101
	v_mul_f32_e32 v98, v98, v102
	v_mul_f32_e32 v99, v99, v103
	v_cvt_pk_bf16_f32 v108, v104, v105
	v_cvt_pk_bf16_f32 v109, v106, v107
	v_cvt_pk_bf16_f32 v110, v96, v97
	v_cvt_pk_bf16_f32 v111, v98, v99
	s_mov_b64 s[28:29], -1
	s_and_b64 vcc, exec, s[8:9]
	v_add_u32_e32 v97, 0xb000, v113
	v_add_lshl_u32 v96, v97, v139, 1
	buffer_store_dwordx4 v[108:111], v96, s[36:39], 0 offen sc1
	s_nop 1
	v_or_b32_e32 v98, 32, v138
	s_cbranch_vccnz .LBB0_803
	v_ashrrev_i32_e32 v99, 31, v98
	v_lshlrev_b64 v[100:101], 6, v[98:99]
	v_lshl_add_u64 v[112:113], s[94:95], 0, v[100:101]
	global_load_dwordx4 v[100:103], v[112:113], off offset:48
	global_load_dwordx4 v[104:107], v[112:113], off offset:32
	global_load_dwordx4 v[108:111], v[112:113], off offset:16
	s_nop 0
	global_load_dwordx4 v[112:115], v[112:113], off
	s_mov_b64 s[28:29], 0
	s_waitcnt vmcnt(0)
	v_add_f32_e32 v104, v104, v105
	v_add_f32_e32 v106, v106, v107
	v_mov_b32_e32 v116, v113
	v_mov_b32_e32 v117, v114
	v_mov_b32_e32 v113, v115
	v_mov_b32_e32 v114, v109
	v_mov_b32_e32 v115, v110
	v_mov_b32_e32 v109, v111
	v_pk_add_f32 v[112:113], v[116:117], v[112:113]
	v_pk_add_f32 v[108:109], v[114:115], v[108:109]
	v_pk_add_f32 v[112:113], v[112:113], v[112:113] op_sel:[0,1] op_sel_hi:[1,0]
	v_pk_add_f32 v[108:109], v[108:109], v[108:109] op_sel:[0,1] op_sel_hi:[1,0]
	v_mov_b32_e32 v113, v100
	v_mov_b32_e32 v109, v101
	v_mov_b32_e32 v105, v102
	v_mov_b32_e32 v107, v103
	v_pk_add_f32 v[100:101], v[112:113], v[108:109]
	v_pk_add_f32 v[102:103], v[104:105], v[106:107]
	s_nop 0
	v_pk_add_f32 v[100:101], v[100:101], v[102:103]
	s_nop 0
	v_add_f32_e32 v96, v100, v101
	v_fmamk_f32 v96, v96, 0x3a800000, v193
	v_cmp_gt_f32_e32 vcc, s40, v96
	v_mul_f32_e32 v99, 0x4b800000, v96
	s_nop 0
	v_cndmask_b32_e32 v96, v96, v99, vcc
	v_rsq_f32_e32 v96, v96
	s_nop 0
	v_mul_f32_e32 v99, 0x45800000, v96
	v_cndmask_b32_e32 v96, v96, v99, vcc

.LBB0_805:
	s_waitcnt lgkmcnt(0)
	v_mul_f32_e32 v92, v92, v96
	v_mul_f32_e32 v93, v93, v96
	v_mul_f32_e32 v94, v94, v96
	v_mul_f32_e32 v95, v95, v96
	v_mul_f32_e32 v84, v84, v96
	v_mul_f32_e32 v85, v85, v96
	v_mul_f32_e32 v86, v86, v96
	v_mul_f32_e32 v87, v87, v96
	v_mul_f32_e32 v88, v88, v96
	v_mul_f32_e32 v89, v89, v96
	v_mul_f32_e32 v90, v90, v96
	v_mul_f32_e32 v91, v91, v96
	v_mul_f32_e32 v80, v80, v96
	v_mul_f32_e32 v81, v81, v96
	v_mul_f32_e32 v82, v82, v96
	v_mul_f32_e32 v83, v83, v96
	v_mul_f32_e32 v88, v88, v92
	v_mul_f32_e32 v89, v89, v93
	v_mul_f32_e32 v90, v90, v94
	v_mul_f32_e32 v91, v91, v95
	v_mul_f32_e32 v80, v80, v84
	v_mul_f32_e32 v81, v81, v85
	v_mul_f32_e32 v82, v82, v86
	v_mul_f32_e32 v83, v83, v87
	v_mul_f32_e32 v92, 0xbfb8aa3b, v92
	v_mul_f32_e32 v93, 0xbfb8aa3b, v93
	v_mul_f32_e32 v94, 0xbfb8aa3b, v94
	v_mul_f32_e32 v95, 0xbfb8aa3b, v95
	v_mul_f32_e32 v84, 0xbfb8aa3b, v84
	v_mul_f32_e32 v85, 0xbfb8aa3b, v85
	v_mul_f32_e32 v86, 0xbfb8aa3b, v86
	v_mul_f32_e32 v87, 0xbfb8aa3b, v87
	v_exp_f32_e32 v92, v92
	v_exp_f32_e32 v93, v93
	v_exp_f32_e32 v94, v94
	v_exp_f32_e32 v95, v95
	v_exp_f32_e32 v84, v84
	v_exp_f32_e32 v85, v85
	v_exp_f32_e32 v86, v86
	v_exp_f32_e32 v87, v87
	v_add_f32_e32 v92, 1.0, v92
	v_add_f32_e32 v93, 1.0, v93
	v_add_f32_e32 v94, 1.0, v94
	v_add_f32_e32 v95, 1.0, v95
	v_add_f32_e32 v84, 1.0, v84
	v_add_f32_e32 v85, 1.0, v85
	v_add_f32_e32 v86, 1.0, v86
	v_add_f32_e32 v87, 1.0, v87
	v_rcp_f32_e32 v92, v92
	v_rcp_f32_e32 v93, v93
	v_rcp_f32_e32 v94, v94
	v_rcp_f32_e32 v95, v95
	v_rcp_f32_e32 v84, v84
	v_rcp_f32_e32 v85, v85
	v_rcp_f32_e32 v86, v86
	v_rcp_f32_e32 v87, v87
	v_mul_f32_e32 v88, v88, v92
	v_mul_f32_e32 v89, v89, v93
	v_mul_f32_e32 v90, v90, v94
	v_mul_f32_e32 v91, v91, v95
	v_mul_f32_e32 v80, v80, v84
	v_mul_f32_e32 v81, v81, v85
	v_mul_f32_e32 v82, v82, v86
	v_mul_f32_e32 v83, v83, v87
	v_cvt_pk_bf16_f32 v92, v88, v89
	v_cvt_pk_bf16_f32 v93, v90, v91
	v_cvt_pk_bf16_f32 v94, v80, v81
	v_cvt_pk_bf16_f32 v95, v82, v83
	s_mov_b64 s[28:29], -1
	s_and_b64 vcc, exec, s[8:9]
	v_add_u32_e32 v81, 0xb000, v97
	v_add_lshl_u32 v80, v81, v139, 1
	buffer_store_dwordx4 v[92:95], v80, s[36:39], 0 offen sc1
	s_nop 1
	v_or_b32_e32 v82, 48, v138
	s_cbranch_vccnz .LBB0_807
	v_ashrrev_i32_e32 v83, 31, v82
	v_lshlrev_b64 v[84:85], 6, v[82:83]
	v_lshl_add_u64 v[96:97], s[94:95], 0, v[84:85]
	global_load_dwordx4 v[84:87], v[96:97], off offset:48
	global_load_dwordx4 v[88:91], v[96:97], off offset:32
	global_load_dwordx4 v[92:95], v[96:97], off offset:16
	s_nop 0
	global_load_dwordx4 v[96:99], v[96:97], off
	s_mov_b64 s[28:29], 0
	s_waitcnt vmcnt(0)
	v_add_f32_e32 v88, v88, v89
	v_add_f32_e32 v90, v90, v91
	v_mov_b32_e32 v100, v97
	v_mov_b32_e32 v101, v98
	v_mov_b32_e32 v97, v99
	v_mov_b32_e32 v98, v93
	v_mov_b32_e32 v99, v94
	v_mov_b32_e32 v93, v95
	v_pk_add_f32 v[96:97], v[100:101], v[96:97]
	v_pk_add_f32 v[92:93], v[98:99], v[92:93]
	v_pk_add_f32 v[96:97], v[96:97], v[96:97] op_sel:[0,1] op_sel_hi:[1,0]
	v_pk_add_f32 v[92:93], v[92:93], v[92:93] op_sel:[0,1] op_sel_hi:[1,0]
	v_mov_b32_e32 v97, v84
	v_mov_b32_e32 v93, v85
	v_mov_b32_e32 v89, v86
	v_mov_b32_e32 v91, v87
	v_pk_add_f32 v[84:85], v[96:97], v[92:93]
	v_pk_add_f32 v[86:87], v[88:89], v[90:91]
	s_nop 0
	v_pk_add_f32 v[84:85], v[84:85], v[86:87]
	s_nop 0
	v_add_f32_e32 v80, v84, v85
	v_fmamk_f32 v80, v80, 0x3a800000, v193
	v_cmp_gt_f32_e32 vcc, s40, v80
	v_mul_f32_e32 v83, 0x4b800000, v80
	s_nop 0
	v_cndmask_b32_e32 v80, v80, v83, vcc
	v_rsq_f32_e32 v80, v80
	s_nop 0
	v_mul_f32_e32 v83, 0x45800000, v80
	v_cndmask_b32_e32 v80, v80, v83, vcc

.LBB0_809:
	s_waitcnt lgkmcnt(0)
	v_mul_f32_e32 v76, v76, v80
	v_mul_f32_e32 v77, v77, v80
	v_mul_f32_e32 v78, v78, v80
	v_mul_f32_e32 v79, v79, v80
	v_mul_f32_e32 v68, v68, v80
	v_mul_f32_e32 v69, v69, v80
	v_mul_f32_e32 v70, v70, v80
	v_mul_f32_e32 v71, v71, v80
	v_mul_f32_e32 v72, v72, v80
	v_mul_f32_e32 v73, v73, v80
	v_mul_f32_e32 v74, v74, v80
	v_mul_f32_e32 v75, v75, v80
	v_mul_f32_e32 v64, v64, v80
	v_mul_f32_e32 v65, v65, v80
	v_mul_f32_e32 v66, v66, v80
	v_mul_f32_e32 v67, v67, v80
	v_mul_f32_e32 v72, v72, v76
	v_mul_f32_e32 v73, v73, v77
	v_mul_f32_e32 v74, v74, v78
	v_mul_f32_e32 v75, v75, v79
	v_mul_f32_e32 v64, v64, v68
	v_mul_f32_e32 v65, v65, v69
	v_mul_f32_e32 v66, v66, v70
	v_mul_f32_e32 v67, v67, v71
	v_mul_f32_e32 v76, 0xbfb8aa3b, v76
	v_mul_f32_e32 v77, 0xbfb8aa3b, v77
	v_mul_f32_e32 v78, 0xbfb8aa3b, v78
	v_mul_f32_e32 v79, 0xbfb8aa3b, v79
	v_mul_f32_e32 v68, 0xbfb8aa3b, v68
	v_mul_f32_e32 v69, 0xbfb8aa3b, v69
	v_mul_f32_e32 v70, 0xbfb8aa3b, v70
	v_mul_f32_e32 v71, 0xbfb8aa3b, v71
	v_exp_f32_e32 v76, v76
	v_exp_f32_e32 v77, v77
	v_exp_f32_e32 v78, v78
	v_exp_f32_e32 v79, v79
	v_exp_f32_e32 v68, v68
	v_exp_f32_e32 v69, v69
	v_exp_f32_e32 v70, v70
	v_exp_f32_e32 v71, v71
	v_add_f32_e32 v76, 1.0, v76
	v_add_f32_e32 v77, 1.0, v77
	v_add_f32_e32 v78, 1.0, v78
	v_add_f32_e32 v79, 1.0, v79
	v_add_f32_e32 v68, 1.0, v68
	v_add_f32_e32 v69, 1.0, v69
	v_add_f32_e32 v70, 1.0, v70
	v_add_f32_e32 v71, 1.0, v71
	v_rcp_f32_e32 v76, v76
	v_rcp_f32_e32 v77, v77
	v_rcp_f32_e32 v78, v78
	v_rcp_f32_e32 v79, v79
	v_rcp_f32_e32 v68, v68
	v_rcp_f32_e32 v69, v69
	v_rcp_f32_e32 v70, v70
	v_rcp_f32_e32 v71, v71
	v_mul_f32_e32 v72, v72, v76
	v_mul_f32_e32 v73, v73, v77
	v_mul_f32_e32 v74, v74, v78
	v_mul_f32_e32 v75, v75, v79
	v_mul_f32_e32 v64, v64, v68
	v_mul_f32_e32 v65, v65, v69
	v_mul_f32_e32 v66, v66, v70
	v_mul_f32_e32 v67, v67, v71
	v_cvt_pk_bf16_f32 v76, v72, v73
	v_cvt_pk_bf16_f32 v77, v74, v75
	v_cvt_pk_bf16_f32 v78, v64, v65
	v_cvt_pk_bf16_f32 v79, v66, v67
	s_mov_b64 s[28:29], -1
	s_and_b64 vcc, exec, s[8:9]
	v_add_u32_e32 v65, 0xb000, v81
	v_add_lshl_u32 v64, v65, v139, 1
	buffer_store_dwordx4 v[76:79], v64, s[36:39], 0 offen sc1
	s_nop 1
	v_add_u32_e32 v66, 0x80, v138
	s_cbranch_vccnz .LBB0_811
	v_ashrrev_i32_e32 v67, 31, v66
	v_lshlrev_b64 v[68:69], 6, v[66:67]
	v_lshl_add_u64 v[80:81], s[94:95], 0, v[68:69]
	global_load_dwordx4 v[68:71], v[80:81], off offset:48
	global_load_dwordx4 v[72:75], v[80:81], off offset:32
	global_load_dwordx4 v[76:79], v[80:81], off offset:16
	s_nop 0
	global_load_dwordx4 v[80:83], v[80:81], off
	s_mov_b64 s[28:29], 0
	s_waitcnt vmcnt(0)
	v_add_f32_e32 v72, v72, v73
	v_add_f32_e32 v74, v74, v75
	v_mov_b32_e32 v84, v81
	v_mov_b32_e32 v85, v82
	v_mov_b32_e32 v81, v83
	v_mov_b32_e32 v82, v77
	v_mov_b32_e32 v83, v78
	v_mov_b32_e32 v77, v79
	v_pk_add_f32 v[80:81], v[84:85], v[80:81]
	v_pk_add_f32 v[76:77], v[82:83], v[76:77]
	v_pk_add_f32 v[80:81], v[80:81], v[80:81] op_sel:[0,1] op_sel_hi:[1,0]
	v_pk_add_f32 v[76:77], v[76:77], v[76:77] op_sel:[0,1] op_sel_hi:[1,0]
	v_mov_b32_e32 v81, v68
	v_mov_b32_e32 v77, v69
	v_mov_b32_e32 v73, v70
	v_mov_b32_e32 v75, v71
	v_pk_add_f32 v[68:69], v[80:81], v[76:77]
	v_pk_add_f32 v[70:71], v[72:73], v[74:75]
	s_nop 0
	v_pk_add_f32 v[68:69], v[68:69], v[70:71]
	s_nop 0
	v_add_f32_e32 v64, v68, v69
	v_fmamk_f32 v64, v64, 0x3a800000, v193
	v_cmp_gt_f32_e32 vcc, s40, v64
	v_mul_f32_e32 v67, 0x4b800000, v64
	s_nop 0
	v_cndmask_b32_e32 v64, v64, v67, vcc
	v_rsq_f32_e32 v64, v64
	s_nop 0
	v_mul_f32_e32 v67, 0x45800000, v64
	v_cndmask_b32_e32 v64, v64, v67, vcc

.LBB0_813:
	s_waitcnt lgkmcnt(0)
	v_mul_f32_e32 v60, v60, v64
	v_mul_f32_e32 v61, v61, v64
	v_mul_f32_e32 v62, v62, v64
	v_mul_f32_e32 v63, v63, v64
	v_mul_f32_e32 v52, v52, v64
	v_mul_f32_e32 v53, v53, v64
	v_mul_f32_e32 v54, v54, v64
	v_mul_f32_e32 v55, v55, v64
	v_mul_f32_e32 v56, v56, v64
	v_mul_f32_e32 v57, v57, v64
	v_mul_f32_e32 v58, v58, v64
	v_mul_f32_e32 v59, v59, v64
	v_mul_f32_e32 v48, v48, v64
	v_mul_f32_e32 v49, v49, v64
	v_mul_f32_e32 v50, v50, v64
	v_mul_f32_e32 v51, v51, v64
	v_mul_f32_e32 v56, v56, v60
	v_mul_f32_e32 v57, v57, v61
	v_mul_f32_e32 v58, v58, v62
	v_mul_f32_e32 v59, v59, v63
	v_mul_f32_e32 v48, v48, v52
	v_mul_f32_e32 v49, v49, v53
	v_mul_f32_e32 v50, v50, v54
	v_mul_f32_e32 v51, v51, v55
	v_mul_f32_e32 v60, 0xbfb8aa3b, v60
	v_mul_f32_e32 v61, 0xbfb8aa3b, v61
	v_mul_f32_e32 v62, 0xbfb8aa3b, v62
	v_mul_f32_e32 v63, 0xbfb8aa3b, v63
	v_mul_f32_e32 v52, 0xbfb8aa3b, v52
	v_mul_f32_e32 v53, 0xbfb8aa3b, v53
	v_mul_f32_e32 v54, 0xbfb8aa3b, v54
	v_mul_f32_e32 v55, 0xbfb8aa3b, v55
	v_exp_f32_e32 v60, v60
	v_exp_f32_e32 v61, v61
	v_exp_f32_e32 v62, v62
	v_exp_f32_e32 v63, v63
	v_exp_f32_e32 v52, v52
	v_exp_f32_e32 v53, v53
	v_exp_f32_e32 v54, v54
	v_exp_f32_e32 v55, v55
	v_add_f32_e32 v60, 1.0, v60
	v_add_f32_e32 v61, 1.0, v61
	v_add_f32_e32 v62, 1.0, v62
	v_add_f32_e32 v63, 1.0, v63
	v_add_f32_e32 v52, 1.0, v52
	v_add_f32_e32 v53, 1.0, v53
	v_add_f32_e32 v54, 1.0, v54
	v_add_f32_e32 v55, 1.0, v55
	v_rcp_f32_e32 v60, v60
	v_rcp_f32_e32 v61, v61
	v_rcp_f32_e32 v62, v62
	v_rcp_f32_e32 v63, v63
	v_rcp_f32_e32 v52, v52
	v_rcp_f32_e32 v53, v53
	v_rcp_f32_e32 v54, v54
	v_rcp_f32_e32 v55, v55
	v_mul_f32_e32 v56, v56, v60
	v_mul_f32_e32 v57, v57, v61
	v_mul_f32_e32 v58, v58, v62
	v_mul_f32_e32 v59, v59, v63
	v_mul_f32_e32 v48, v48, v52
	v_mul_f32_e32 v49, v49, v53
	v_mul_f32_e32 v50, v50, v54
	v_mul_f32_e32 v51, v51, v55
	v_cvt_pk_bf16_f32 v60, v56, v57
	v_cvt_pk_bf16_f32 v61, v58, v59
	v_cvt_pk_bf16_f32 v62, v48, v49
	v_cvt_pk_bf16_f32 v63, v50, v51
	s_mov_b64 s[28:29], -1
	s_and_b64 vcc, exec, s[8:9]
	v_add_u32_e32 v49, 0x37000, v65
	v_add_lshl_u32 v48, v49, v139, 1
	buffer_store_dwordx4 v[60:63], v48, s[36:39], 0 offen sc1
	s_nop 1
	v_add_u32_e32 v50, 0x90, v138
	s_cbranch_vccnz .LBB0_815
	v_ashrrev_i32_e32 v51, 31, v50
	v_lshlrev_b64 v[52:53], 6, v[50:51]
	v_lshl_add_u64 v[64:65], s[94:95], 0, v[52:53]
	global_load_dwordx4 v[52:55], v[64:65], off offset:48
	global_load_dwordx4 v[56:59], v[64:65], off offset:32
	global_load_dwordx4 v[60:63], v[64:65], off offset:16
	s_nop 0
	global_load_dwordx4 v[64:67], v[64:65], off
	s_mov_b64 s[28:29], 0
	s_waitcnt vmcnt(0)
	v_add_f32_e32 v56, v56, v57
	v_add_f32_e32 v58, v58, v59
	v_mov_b32_e32 v68, v65
	v_mov_b32_e32 v69, v66
	v_mov_b32_e32 v65, v67
	v_mov_b32_e32 v66, v61
	v_mov_b32_e32 v67, v62
	v_mov_b32_e32 v61, v63
	v_pk_add_f32 v[64:65], v[68:69], v[64:65]
	v_pk_add_f32 v[60:61], v[66:67], v[60:61]
	v_pk_add_f32 v[64:65], v[64:65], v[64:65] op_sel:[0,1] op_sel_hi:[1,0]
	v_pk_add_f32 v[60:61], v[60:61], v[60:61] op_sel:[0,1] op_sel_hi:[1,0]
	v_mov_b32_e32 v65, v52
	v_mov_b32_e32 v61, v53
	v_mov_b32_e32 v57, v54
	v_mov_b32_e32 v59, v55
	v_pk_add_f32 v[52:53], v[64:65], v[60:61]
	v_pk_add_f32 v[54:55], v[56:57], v[58:59]
	s_nop 0
	v_pk_add_f32 v[52:53], v[52:53], v[54:55]
	s_nop 0
	v_add_f32_e32 v48, v52, v53
	v_fmamk_f32 v48, v48, 0x3a800000, v193
	v_cmp_gt_f32_e32 vcc, s40, v48
	v_mul_f32_e32 v51, 0x4b800000, v48
	s_nop 0
	v_cndmask_b32_e32 v48, v48, v51, vcc
	v_rsq_f32_e32 v48, v48
	s_nop 0
	v_mul_f32_e32 v51, 0x45800000, v48
	v_cndmask_b32_e32 v48, v48, v51, vcc

.LBB0_817:
	s_waitcnt lgkmcnt(0)
	v_mul_f32_e32 v44, v44, v48
	v_mul_f32_e32 v45, v45, v48
	v_mul_f32_e32 v46, v46, v48
	v_mul_f32_e32 v47, v47, v48
	v_mul_f32_e32 v36, v36, v48
	v_mul_f32_e32 v37, v37, v48
	v_mul_f32_e32 v38, v38, v48
	v_mul_f32_e32 v39, v39, v48
	v_mul_f32_e32 v40, v40, v48
	v_mul_f32_e32 v41, v41, v48
	v_mul_f32_e32 v42, v42, v48
	v_mul_f32_e32 v43, v43, v48
	v_mul_f32_e32 v32, v32, v48
	v_mul_f32_e32 v33, v33, v48
	v_mul_f32_e32 v34, v34, v48
	v_mul_f32_e32 v35, v35, v48
	v_mul_f32_e32 v40, v40, v44
	v_mul_f32_e32 v41, v41, v45
	v_mul_f32_e32 v42, v42, v46
	v_mul_f32_e32 v43, v43, v47
	v_mul_f32_e32 v32, v32, v36
	v_mul_f32_e32 v33, v33, v37
	v_mul_f32_e32 v34, v34, v38
	v_mul_f32_e32 v35, v35, v39
	v_mul_f32_e32 v44, 0xbfb8aa3b, v44
	v_mul_f32_e32 v45, 0xbfb8aa3b, v45
	v_mul_f32_e32 v46, 0xbfb8aa3b, v46
	v_mul_f32_e32 v47, 0xbfb8aa3b, v47
	v_mul_f32_e32 v36, 0xbfb8aa3b, v36
	v_mul_f32_e32 v37, 0xbfb8aa3b, v37
	v_mul_f32_e32 v38, 0xbfb8aa3b, v38
	v_mul_f32_e32 v39, 0xbfb8aa3b, v39
	v_exp_f32_e32 v44, v44
	v_exp_f32_e32 v45, v45
	v_exp_f32_e32 v46, v46
	v_exp_f32_e32 v47, v47
	v_exp_f32_e32 v36, v36
	v_exp_f32_e32 v37, v37
	v_exp_f32_e32 v38, v38
	v_exp_f32_e32 v39, v39
	v_add_f32_e32 v44, 1.0, v44
	v_add_f32_e32 v45, 1.0, v45
	v_add_f32_e32 v46, 1.0, v46
	v_add_f32_e32 v47, 1.0, v47
	v_add_f32_e32 v36, 1.0, v36
	v_add_f32_e32 v37, 1.0, v37
	v_add_f32_e32 v38, 1.0, v38
	v_add_f32_e32 v39, 1.0, v39
	v_rcp_f32_e32 v44, v44
	v_rcp_f32_e32 v45, v45
	v_rcp_f32_e32 v46, v46
	v_rcp_f32_e32 v47, v47
	v_rcp_f32_e32 v36, v36
	v_rcp_f32_e32 v37, v37
	v_rcp_f32_e32 v38, v38
	v_rcp_f32_e32 v39, v39
	v_mul_f32_e32 v40, v40, v44
	v_mul_f32_e32 v41, v41, v45
	v_mul_f32_e32 v42, v42, v46
	v_mul_f32_e32 v43, v43, v47
	v_mul_f32_e32 v32, v32, v36
	v_mul_f32_e32 v33, v33, v37
	v_mul_f32_e32 v34, v34, v38
	v_mul_f32_e32 v35, v35, v39
	v_cvt_pk_bf16_f32 v44, v40, v41
	v_cvt_pk_bf16_f32 v45, v42, v43
	v_cvt_pk_bf16_f32 v46, v32, v33
	v_cvt_pk_bf16_f32 v47, v34, v35
	s_mov_b64 s[28:29], -1
	s_and_b64 vcc, exec, s[8:9]
	v_add_u32_e32 v35, 0xb000, v49
	v_add_lshl_u32 v32, v35, v139, 1
	buffer_store_dwordx4 v[44:47], v32, s[36:39], 0 offen sc1
	v_add_u32_e32 v32, 0xa0, v138
	s_cbranch_vccnz .LBB0_819
	v_ashrrev_i32_e32 v33, 31, v32
	v_lshlrev_b64 v[36:37], 6, v[32:33]
	v_lshl_add_u64 v[48:49], s[94:95], 0, v[36:37]
	global_load_dwordx4 v[36:39], v[48:49], off offset:48
	global_load_dwordx4 v[40:43], v[48:49], off offset:32
	global_load_dwordx4 v[44:47], v[48:49], off offset:16
	s_nop 0
	global_load_dwordx4 v[48:51], v[48:49], off
	s_mov_b64 s[28:29], 0
	s_waitcnt vmcnt(0)
	v_add_f32_e32 v40, v40, v41
	v_add_f32_e32 v42, v42, v43
	v_mov_b32_e32 v52, v49
	v_mov_b32_e32 v53, v50
	v_mov_b32_e32 v49, v51
	v_mov_b32_e32 v50, v45
	v_mov_b32_e32 v51, v46
	v_mov_b32_e32 v45, v47
	v_pk_add_f32 v[48:49], v[52:53], v[48:49]
	v_pk_add_f32 v[44:45], v[50:51], v[44:45]
	v_pk_add_f32 v[48:49], v[48:49], v[48:49] op_sel:[0,1] op_sel_hi:[1,0]
	v_pk_add_f32 v[44:45], v[44:45], v[44:45] op_sel:[0,1] op_sel_hi:[1,0]
	v_mov_b32_e32 v49, v36
	v_mov_b32_e32 v45, v37
	v_mov_b32_e32 v41, v38
	v_mov_b32_e32 v43, v39
	v_pk_add_f32 v[36:37], v[48:49], v[44:45]
	v_pk_add_f32 v[38:39], v[40:41], v[42:43]
	s_nop 0
	v_pk_add_f32 v[36:37], v[36:37], v[38:39]
	s_nop 0
	v_add_f32_e32 v33, v36, v37
	v_fmamk_f32 v33, v33, 0x3a800000, v193
	v_cmp_gt_f32_e32 vcc, s40, v33
	v_mul_f32_e32 v34, 0x4b800000, v33
	s_nop 0
	v_cndmask_b32_e32 v33, v33, v34, vcc
	v_rsq_f32_e32 v33, v33
	s_nop 0
	v_mul_f32_e32 v34, 0x45800000, v33
	v_cndmask_b32_e32 v34, v33, v34, vcc

.LBB0_821:
	s_waitcnt lgkmcnt(0)
	v_mul_f32_e32 v28, v28, v34
	v_mul_f32_e32 v29, v29, v34
	v_mul_f32_e32 v30, v30, v34
	v_mul_f32_e32 v31, v31, v34
	v_mul_f32_e32 v20, v20, v34
	v_mul_f32_e32 v21, v21, v34
	v_mul_f32_e32 v22, v22, v34
	v_mul_f32_e32 v23, v23, v34
	v_mul_f32_e32 v24, v24, v34
	v_mul_f32_e32 v25, v25, v34
	v_mul_f32_e32 v26, v26, v34
	v_mul_f32_e32 v27, v27, v34
	v_mul_f32_e32 v16, v16, v34
	v_mul_f32_e32 v17, v17, v34
	v_mul_f32_e32 v18, v18, v34
	v_mul_f32_e32 v19, v19, v34
	v_mul_f32_e32 v24, v24, v28
	v_mul_f32_e32 v25, v25, v29
	v_mul_f32_e32 v26, v26, v30
	v_mul_f32_e32 v27, v27, v31
	v_mul_f32_e32 v16, v16, v20
	v_mul_f32_e32 v17, v17, v21
	v_mul_f32_e32 v18, v18, v22
	v_mul_f32_e32 v19, v19, v23
	v_mul_f32_e32 v28, 0xbfb8aa3b, v28
	v_mul_f32_e32 v29, 0xbfb8aa3b, v29
	v_mul_f32_e32 v30, 0xbfb8aa3b, v30
	v_mul_f32_e32 v31, 0xbfb8aa3b, v31
	v_mul_f32_e32 v20, 0xbfb8aa3b, v20
	v_mul_f32_e32 v21, 0xbfb8aa3b, v21
	v_mul_f32_e32 v22, 0xbfb8aa3b, v22
	v_mul_f32_e32 v23, 0xbfb8aa3b, v23
	v_exp_f32_e32 v28, v28
	v_exp_f32_e32 v29, v29
	v_exp_f32_e32 v30, v30
	v_exp_f32_e32 v31, v31
	v_exp_f32_e32 v20, v20
	v_exp_f32_e32 v21, v21
	v_exp_f32_e32 v22, v22
	v_exp_f32_e32 v23, v23
	v_add_f32_e32 v28, 1.0, v28
	v_add_f32_e32 v29, 1.0, v29
	v_add_f32_e32 v30, 1.0, v30
	v_add_f32_e32 v31, 1.0, v31
	v_add_f32_e32 v20, 1.0, v20
	v_add_f32_e32 v21, 1.0, v21
	v_add_f32_e32 v22, 1.0, v22
	v_add_f32_e32 v23, 1.0, v23
	v_rcp_f32_e32 v28, v28
	v_rcp_f32_e32 v29, v29
	v_rcp_f32_e32 v30, v30
	v_rcp_f32_e32 v31, v31
	v_rcp_f32_e32 v20, v20
	v_rcp_f32_e32 v21, v21
	v_rcp_f32_e32 v22, v22
	v_rcp_f32_e32 v23, v23
	v_mul_f32_e32 v24, v24, v28
	v_mul_f32_e32 v25, v25, v29
	v_mul_f32_e32 v26, v26, v30
	v_mul_f32_e32 v27, v27, v31
	v_mul_f32_e32 v16, v16, v20
	v_mul_f32_e32 v17, v17, v21
	v_mul_f32_e32 v18, v18, v22
	v_mul_f32_e32 v19, v19, v23
	v_cvt_pk_bf16_f32 v28, v24, v25
	v_cvt_pk_bf16_f32 v29, v26, v27
	v_cvt_pk_bf16_f32 v30, v16, v17
	v_cvt_pk_bf16_f32 v31, v18, v19
	s_and_b64 vcc, exec, s[8:9]
	s_mov_b64 s[8:9], -1
	v_add_u32_e32 v17, 0xb000, v35
	v_add_lshl_u32 v16, v17, v139, 1
	buffer_store_dwordx4 v[28:31], v16, s[36:39], 0 offen sc1
	s_nop 1
	v_add_u32_e32 v18, 0xb0, v138
	s_cbranch_vccnz .LBB0_823
	v_ashrrev_i32_e32 v19, 31, v18
	v_lshlrev_b64 v[20:21], 6, v[18:19]
	v_lshl_add_u64 v[32:33], s[94:95], 0, v[20:21]
	global_load_dwordx4 v[20:23], v[32:33], off offset:48
	global_load_dwordx4 v[24:27], v[32:33], off offset:32
	global_load_dwordx4 v[28:31], v[32:33], off offset:16
	s_nop 0
	global_load_dwordx4 v[32:35], v[32:33], off
	s_mov_b64 s[8:9], 0
	s_waitcnt vmcnt(0)
	v_add_f32_e32 v24, v24, v25
	v_add_f32_e32 v26, v26, v27
	v_mov_b32_e32 v36, v33
	v_mov_b32_e32 v37, v34
	v_mov_b32_e32 v33, v35
	v_mov_b32_e32 v34, v29
	v_mov_b32_e32 v35, v30
	v_mov_b32_e32 v29, v31
	v_pk_add_f32 v[32:33], v[36:37], v[32:33]
	v_pk_add_f32 v[28:29], v[34:35], v[28:29]
	v_pk_add_f32 v[32:33], v[32:33], v[32:33] op_sel:[0,1] op_sel_hi:[1,0]
	v_pk_add_f32 v[28:29], v[28:29], v[28:29] op_sel:[0,1] op_sel_hi:[1,0]
	v_mov_b32_e32 v33, v20
	v_mov_b32_e32 v29, v21
	v_mov_b32_e32 v25, v22
	v_mov_b32_e32 v27, v23
	v_pk_add_f32 v[20:21], v[32:33], v[28:29]
	v_pk_add_f32 v[22:23], v[24:25], v[26:27]
	s_nop 0
	v_pk_add_f32 v[20:21], v[20:21], v[22:23]
	s_nop 0
	v_add_f32_e32 v16, v20, v21
	v_fmamk_f32 v16, v16, 0x3a800000, v193
	v_cmp_gt_f32_e32 vcc, s40, v16
	v_mul_f32_e32 v19, 0x4b800000, v16
	s_nop 0
	v_cndmask_b32_e32 v16, v16, v19, vcc
	v_rsq_f32_e32 v16, v16
	s_nop 0
	v_mul_f32_e32 v19, 0x45800000, v16
	v_cndmask_b32_e32 v16, v16, v19, vcc
